# FFN2 up/down weight conversion moved from P4 to the 96 CUs idle in P9 (gate stays in P4)
# speedup vs baseline: 1.0094x; 1.0041x over previous
; #define LAS __attribute__((address_space(3)))
; __device__ __forceinline__ unsigned pk2(float lo, float hi) { f32x2_t v = {lo, hi}; bf16x2_t b = __builtin_convertvector(v, bf16x2_t); return __builtin_bit_cast(unsigned, b); }
; #define CVT_DECODE_P4(J, it_) do { int r = (it_); J.ok = false; \
;             CVT_DEC(J, args.in[28], D, FF, WGU, 1, args.in[27]) CVT_DEC(J, args.in[29], D, FF, WGU, 2, args.in[27]) CVT_DEC(J, args.in[30], FF, D, WD, 0, nogam) } while (0)
; __device__ __forceinline__ void cvt_to_lds(const f32x4 (&cv)[8], LAS unsigned char* lds, int wave, int lane) {
; #pragma unroll
;     for (int i = 0; i < 8; ++i) { const int k = wave + 8 * i; *(LAS f32x4*)(lds + (size_t)k * 1024 + (((4 * lane) ^ (4 * (k >> 3))) * 4)) = cv[i]; }
; }
; __device__ __forceinline__ void cvt_from_lds(const CvtJob& J, LAS unsigned char* lds, int tid) {
;     const int nblk = (J.N + 255) / 256, kb = J.item / nblk, nb = J.item % nblk, k0 = 64 * kb, n0 = 256 * nb;
; #pragma unroll
;     for (int j = 0; j < 4; ++j) {
;         const int q = tid + 512 * j, n = q >> 3, c = q & 7;
;         const LAS float* sp = (const LAS float*)lds + (8 * c) * 256 + (n ^ (4 * c));
;         u32x4 o; o.x = pk2(sp[0 * 256], sp[1 * 256]); o.y = pk2(sp[2 * 256], sp[3 * 256]); o.z = pk2(sp[4 * 256], sp[5 * 256]); o.w = pk2(sp[6 * 256], sp[7 * 256]);
;         if (n0 + n < J.N) *(u32x4*)(J.WT + (size_t)cvt_row(J.kind, n0 + n) * J.K + k0 + 8 * c) = o;
;     }
; }
; __global__ void __launch_bounds__(512, 2) mega_fwd(Args args) {
;     ...
; #pragma unroll 1
;         for (int rep = 0; rep < args.ph_lo + 1 + DUP_CVT4; ++rep)
;         {
;             CvtJob cur, nxt; f32x4 cv[8]; int it = cu;
;             CVT_DECODE_P4(cur, it); if (cur.ok) cvt_load(cur, cv, wave, lane);
;             while (cur.ok) {
;                 cvt_to_lds(cv, lds, wave, lane);
;                 __syncthreads();
;                 it += G; CVT_DECODE_P4(nxt, it); if (nxt.ok) cvt_load(nxt, cv, wave, lane);
.LBB0_606:
	s_andn2_b64 vcc, exec, s[4:5]
	s_cbranch_vccnz .LBB0_805
	s_cmp_eq_u32 s15, 0x100
	s_cselect_b32 s94, 2, 0
.Lcvt_entry:
	s_cmpk_gt_i32 s80, 0x2bf
	s_cselect_b64 s[0:1], -1, 0
	s_add_i32 s68, s80, 0xfffffd40
	s_cmpk_lt_i32 s80, 0x2c0
	s_cselect_b32 s4, s80, s68
	s_add_i32 s5, s4, 0xfffffd40
	s_cmpk_lt_i32 s4, 0x2c0
	s_cselect_b64 s[36:37], -1, 0
	s_and_b64 s[2:3], s[36:37], exec
	s_cselect_b32 s69, s4, s5
	s_lshl_b32 s2, s90, 10
	v_lshlrev_b32_e32 v0, 4, v184
	s_add_i32 s6, s2, 0
	s_lshl_b32 s2, s90, 1
	v_mov_b32_e32 v2, 0x7fffff0
	v_bitop3_b32 v32, s2, v0, v2 bitop3:0x6c
	s_add_i32 s2, s90, 8
	s_lshl_b32 s3, s2, 10
	s_lshl_b32 s2, s2, 1
	v_mov_b32_e32 v2, 0xffffff0
	v_bitop3_b32 v33, s2, v0, v2 bitop3:0x6c
	s_add_i32 s2, s90, 16
	s_add_i32 s7, s3, 0
	s_lshl_b32 s3, s2, 10
	s_lshl_b32 s2, s2, 1
	v_bitop3_b32 v38, s2, v0, v2 bitop3:0x6c
	s_add_i32 s2, s90, 24
	s_add_i32 s8, s3, 0
	s_lshl_b32 s3, s2, 10
	s_lshl_b32 s2, s2, 1
	v_bitop3_b32 v39, s2, v0, v2 bitop3:0x6c
	s_add_i32 s2, s90, 32
	s_add_i32 s9, s3, 0
	s_lshl_b32 s3, s2, 10
	s_lshl_b32 s2, s2, 1
	v_bitop3_b32 v40, s2, v0, v2 bitop3:0x6c
	s_add_i32 s2, s90, 40
	s_add_i32 s10, s3, 0
	s_lshl_b32 s3, s2, 10
	s_lshl_b32 s2, s2, 1
	v_bitop3_b32 v41, s2, v0, v2 bitop3:0x6c
	s_add_i32 s2, s90, 48
	s_add_i32 s11, s3, 0
	s_lshl_b32 s3, s2, 10
	s_lshl_b32 s2, s2, 1
	v_bitop3_b32 v42, s2, v0, v2 bitop3:0x6c
	s_add_i32 s2, s90, 56
	s_add_i32 s12, s3, 0
	s_lshl_b32 s3, s2, 10
	s_lshl_b32 s2, s2, 1
	v_bitop3_b32 v43, s2, v0, v2 bitop3:0x6c
	v_and_b32_e32 v0, 7, v185
	v_lshlrev_b32_e32 v3, 2, v0
	v_lshrrev_b32_e32 v35, 3, v185
	v_lshl_add_u32 v2, v0, 13, 0
	v_lshlrev_b32_e32 v36, 3, v0
	v_xor_b32_e32 v0, v3, v35
	v_lshl_add_u32 v37, v0, 2, v2
	s_movk_i32 s4, 0x80
	v_add_u32_e32 v0, 0x200, v185
	v_lshrrev_b32_e32 v47, 3, v0
	v_bfe_u32 v50, v0, 3, 7
	v_bitop3_b32 v0, v35, v3, s4 bitop3:0x36
	v_lshl_add_u32 v51, v0, 2, v2
	v_add_u32_e32 v0, 0x600, v185
	v_lshrrev_b32_e32 v53, 3, v0
	v_mov_b32_e32 v1, 0
	v_xor_b32_e32 v4, v47, v3
	v_xor_b32_e32 v3, v53, v3
	v_lshl_add_u32 v48, v4, 2, v2
	v_lshl_add_u32 v54, v3, 2, v2
	v_mov_b32_e32 v2, v1
	v_mov_b32_e32 v3, v1
	v_mov_b32_e32 v4, v1
	v_mov_b32_e32 v5, v1
	v_mov_b32_e32 v6, v1
	v_mov_b32_e32 v7, v1
	v_mov_b32_e32 v8, v1
	v_mov_b32_e32 v9, v1
	v_mov_b32_e32 v10, v1
	v_mov_b32_e32 v11, v1
	v_mov_b32_e32 v12, v1
	v_mov_b32_e32 v13, v1
	v_mov_b32_e32 v14, v1
	v_mov_b32_e32 v15, v1
	v_mov_b32_e32 v16, v1
	v_mov_b32_e32 v17, v1
	v_mov_b32_e32 v18, v1
	v_mov_b32_e32 v19, v1
	v_mov_b32_e32 v20, v1
	v_mov_b32_e32 v21, v1
	v_mov_b32_e32 v22, v1
	v_mov_b32_e32 v23, v1
	v_mov_b32_e32 v24, v1
	v_mov_b32_e32 v25, v1
	v_mov_b32_e32 v26, v1
	v_mov_b32_e32 v27, v1
	v_mov_b32_e32 v28, v1
	v_mov_b32_e32 v29, v1
	v_mov_b32_e32 v30, v1
	v_mov_b32_e32 v31, v1
	s_add_i32 s13, s3, 0
	s_movk_i32 s2, 0x1ff
	v_bfe_u32 v55, v0, 3, 8
	s_movk_i32 s4, 0x7f
	v_bfe_u32 v57, v0, 3, 7
	v_mov_b32_e32 v0, v1
	v_add_u32_e32 v60, s6, v32
	v_add_u32_e32 v61, s7, v33
	v_mov_b64_e32 v[32:33], v[30:31]
	v_lshlrev_b32_e32 v34, 2, v184
	v_or_b32_e32 v46, 0x80, v35
	v_cmp_lt_u32_e64 s[2:3], s2, v185
	v_add_u32_e32 v49, 0x380, v47
	v_or_b32_e32 v52, 0x400, v35
	v_cmp_lt_u32_e64 s[4:5], s4, v55
	v_add_u32_e32 v56, 0x380, v55
	v_or_b32_e32 v58, 0x80, v47
	v_or_b32_e32 v59, 0x80, v57
	s_add_i32 s70, s80, s15
	s_mov_b32 s71, 0
	v_add_u32_e32 v62, s8, v38
	v_add_u32_e32 v63, s9, v39
	v_add_u32_e32 v64, s10, v40
	v_add_u32_e32 v65, s11, v41
	v_add_u32_e32 v66, s12, v42
	v_add_u32_e32 v67, s13, v43
	s_movk_i32 s72, 0x73f
	s_movk_i32 s73, 0xb3f
	s_movk_i32 s74, 0xff00
	v_mov_b64_e32 v[30:31], v[28:29]
	v_mov_b64_e32 v[28:29], v[26:27]
	v_mov_b64_e32 v[26:27], v[24:25]
	v_mov_b64_e32 v[24:25], v[22:23]
	v_mov_b64_e32 v[22:23], v[20:21]
	v_mov_b64_e32 v[20:21], v[18:19]
	v_mov_b64_e32 v[18:19], v[16:17]
	v_mov_b64_e32 v[16:17], v[14:15]
	v_mov_b64_e32 v[14:15], v[12:13]
	v_mov_b64_e32 v[12:13], v[10:11]
	v_mov_b64_e32 v[10:11], v[8:9]
	v_mov_b64_e32 v[8:9], v[6:7]
	v_mov_b64_e32 v[6:7], v[4:5]
	v_mov_b64_e32 v[4:5], v[2:3]
	v_mov_b64_e32 v[2:3], v[0:1]
	s_branch .LBB0_610

; #define LAS __attribute__((address_space(3)))
; #define CVT_DECODE_P4(J, it_) do { int r = (it_); J.ok = false; \
;             CVT_DEC(J, args.in[28], D, FF, WGU, 1, args.in[27]) CVT_DEC(J, args.in[29], D, FF, WGU, 2, args.in[27]) CVT_DEC(J, args.in[30], FF, D, WD, 0, nogam) } while (0)
; __device__ __forceinline__ void cvt_load(const CvtJob& J, f32x4 (&cv)[8], int wave, int lane) {
;     ...
;         if (J.gam) cv[i] = cv[i] * J.gam[k]; }
; __device__ __forceinline__ void cvt_to_lds(const f32x4 (&cv)[8], LAS unsigned char* lds, int wave, int lane) {
;     ...
;     for (int i = 0; i < 8; ++i) { const int k = wave + 8 * i; *(LAS f32x4*)(lds + (size_t)k * 1024 + (((4 * lane) ^ (4 * (k >> 3))) * 4)) = cv[i]; }
; __global__ void __launch_bounds__(512, 2) mega_fwd(Args args) {
;     ...
;                 cvt_to_lds(cv, lds, wave, lane);
;                 __syncthreads();
;                 it += G; CVT_DECODE_P4(nxt, it); if (nxt.ok) cvt_load(nxt, cv, wave, lane);
.LBB0_649:
	s_cmpk_lt_i32 s16, 0x2c0
	s_mov_b64 s[6:7], -1
	s_waitcnt vmcnt(0)
	v_pk_mul_f32 v[4:5], v[4:5], v[70:71] op_sel_hi:[1,0]
	v_pk_mul_f32 v[2:3], v[2:3], v[70:71] op_sel_hi:[1,0]
	v_pk_mul_f32 v[8:9], v[8:9], v[72:73] op_sel_hi:[1,0]
	v_pk_mul_f32 v[6:7], v[6:7], v[72:73] op_sel_hi:[1,0]
	v_pk_mul_f32 v[12:13], v[12:13], v[74:75] op_sel_hi:[1,0]
	v_pk_mul_f32 v[10:11], v[10:11], v[74:75] op_sel_hi:[1,0]
	v_pk_mul_f32 v[16:17], v[16:17], v[76:77] op_sel_hi:[1,0]
	v_pk_mul_f32 v[14:15], v[14:15], v[76:77] op_sel_hi:[1,0]
	v_pk_mul_f32 v[20:21], v[20:21], v[78:79] op_sel_hi:[1,0]
	v_pk_mul_f32 v[18:19], v[18:19], v[78:79] op_sel_hi:[1,0]
	v_pk_mul_f32 v[24:25], v[24:25], v[80:81] op_sel_hi:[1,0]
	v_pk_mul_f32 v[22:23], v[22:23], v[80:81] op_sel_hi:[1,0]
	v_pk_mul_f32 v[28:29], v[28:29], v[82:83] op_sel_hi:[1,0]
	v_pk_mul_f32 v[26:27], v[26:27], v[82:83] op_sel_hi:[1,0]
	v_pk_mul_f32 v[32:33], v[32:33], v[84:85] op_sel_hi:[1,0]
	v_pk_mul_f32 v[30:31], v[30:31], v[84:85] op_sel_hi:[1,0]
	v_mov_b32_e32 v70, 1.0
	v_mov_b32_e32 v72, 1.0
	v_mov_b32_e32 v74, 1.0
	v_mov_b32_e32 v76, 1.0
	v_mov_b32_e32 v78, 1.0
	v_mov_b32_e32 v80, 1.0
	v_mov_b32_e32 v82, 1.0
	v_mov_b32_e32 v84, 1.0
	ds_write_b128 v60, v[2:5]
	ds_write_b128 v61, v[6:9]
	ds_write_b128 v62, v[10:13]
	ds_write_b128 v63, v[14:17]
	ds_write_b128 v64, v[18:21]
	ds_write_b128 v65, v[22:25]
	ds_write_b128 v66, v[26:29]
	ds_write_b128 v67, v[30:33]
	s_waitcnt lgkmcnt(0)
	s_barrier
	s_cbranch_scc1 .LBB0_651
	s_cmp_eq_u32 s94, 2
	s_cbranch_scc1 .Lcvt_stop
	s_add_i32 s12, s16, 0xfffffd40
	s_cmpk_lt_u32 s12, 0x2c0
	s_cselect_b64 s[8:9], -1, 0
	s_add_i32 s13, s16, 0xfffffa80
	s_and_b64 s[10:11], s[8:9], exec
	s_cselect_b32 s55, s27, s55
	s_cselect_b32 s54, s26, s54
	s_cselect_b32 s53, s87, s53
	s_cselect_b32 s52, s86, s52
	s_cselect_b32 s45, s23, s45
	s_cselect_b32 s44, s22, s44
	s_cselect_b32 s77, 0x800, s77
	s_cselect_b32 s76, 0x1600, s76
	s_cselect_b32 s75, 2, s75
	s_cselect_b32 s78, s12, s78
	s_cselect_b32 s10, s12, s13
	s_and_b64 vcc, exec, s[8:9]
	s_cbranch_vccz .LBB0_652
	s_branch .LBB0_654
.Lcvt_stop:
	s_mov_b64 s[6:7], 0
	s_branch .LBB0_654

; #define CVT_DECODE_P4(J, it_) do { int r = (it_); J.ok = false; \
;             CVT_DEC(J, args.in[28], D, FF, WGU, 1, args.in[27]) CVT_DEC(J, args.in[29], D, FF, WGU, 2, args.in[27]) CVT_DEC(J, args.in[30], FF, D, WD, 0, nogam) } while (0)
; __global__ void __launch_bounds__(512, 2) mega_fwd(Args args) {
;     ...
;             while (cur.ok) {
;                 cvt_to_lds(cv, lds, wave, lane);
;                 __syncthreads();
;                 it += G; CVT_DECODE_P4(nxt, it); if (nxt.ok) cvt_load(nxt, cv, wave, lane);
;                 cvt_from_lds(cur, lds, tid);
;                 __syncthreads();
;                 cur = nxt;
;             }
;         }
.Lcvt_exit:
	s_cmp_eq_u32 s94, 1
	s_cbranch_scc1 .Lp9c_ret

; #define CVT_DECODE_P4(J, it_) do { int r = (it_); J.ok = false; \
;             CVT_DEC(J, args.in[28], D, FF, WGU, 1, args.in[27]) CVT_DEC(J, args.in[29], D, FF, WGU, 2, args.in[27]) CVT_DEC(J, args.in[30], FF, D, WD, 0, nogam) } while (0)
; __global__ void __launch_bounds__(512, 2) mega_fwd(Args args) {
;     ...
; #pragma unroll 1
;         for (int rep = 0; rep < args.ph_lo + 1 + DUP_CVT4; ++rep)
;         {
;             CvtJob cur, nxt; f32x4 cv[8]; int it = cu;
;             CVT_DECODE_P4(cur, it); if (cur.ok) cvt_load(cur, cv, wave, lane);
;             while (cur.ok) {
;                 cvt_to_lds(cv, lds, wave, lane);
;                 __syncthreads();
;                 it += G; CVT_DECODE_P4(nxt, it); if (nxt.ok) cvt_load(nxt, cv, wave, lane);
;                 cvt_from_lds(cur, lds, tid);
;                 __syncthreads();
;                 cur = nxt;
;             }
;         }
;     ...
;     if (IN(9)) {
;         { pg8::Gemm g{XB2, WMQ, D, D, D}; pg8::StaticOrder S; S.init(T, 512, G, cu); pg8::EpiStore E{MQ, 512, 0, SS2, 1}; pg8::gemm_phase(lds, g, S, E); }
;         { pg8::Gemm g{MEMN, WMKV, D, D, D}; pg8::StaticOrder S; S.init(NB * 256, 512, G, (cu + 128) % G); pg8::EpiStore E{MK, 512, 0, nullptr, 0}; pg8::gemm_phase(lds, g, S, E); }
;         { pg8::Gemm g{WMKV + (size_t)512 * D, MEMN, D, D, D}; pg8::StaticOrder S; S.init(512, NB * 256, G, (cu + 96) % G); pg8::EpiStore E{MVT, NB * 256, 0, nullptr, 0}; pg8::gemm_phase(lds, g, S, E); }
;     }
.LBB0_1282:
	s_cmp_lt_i32 s92, 10
	s_cselect_b64 s[0:1], -1, 0
	s_add_u32 s22, s86, 0x15100000
	s_addc_u32 s23, s87, 0
	s_add_u32 s24, s86, 0x15300000
	s_addc_u32 s25, s87, 0
	s_and_b64 s[4:5], s[0:1], s[2:3]
	s_andn2_b64 vcc, exec, s[4:5]
	s_cbranch_vccnz .LBB0_1355
	s_cmp_lg_u32 s15, 0x100
	s_cbranch_scc1 .Lp9c_skip
	s_cmpk_lt_i32 s80, 0x90
	s_cbranch_scc1 .Lp9c_skip
	s_add_i32 s95, s80, 0xffffff70
	s_cmpk_lt_i32 s80, 0xa0
	s_cbranch_scc1 .Lp9c_go
	s_cmpk_lt_i32 s80, 0xb0
	s_cbranch_scc1 .Lp9c_skip
	s_add_i32 s95, s80, 0xffffff60
.Lp9c_go:
	v_writelane_b32 v237, s4, 0
	v_writelane_b32 v237, s5, 1
	v_writelane_b32 v237, s6, 2
	v_writelane_b32 v237, s7, 3
	v_writelane_b32 v237, s8, 4
	v_writelane_b32 v237, s9, 5
	v_writelane_b32 v237, s10, 6
	v_writelane_b32 v237, s11, 7
	v_writelane_b32 v237, s12, 8
	v_writelane_b32 v237, s22, 9
	v_writelane_b32 v237, s23, 10
	v_writelane_b32 v237, s24, 11
	v_writelane_b32 v237, s25, 12
	v_writelane_b32 v237, s26, 13
	v_writelane_b32 v237, s27, 14
	v_writelane_b32 v237, s28, 15
	v_writelane_b32 v237, s29, 16
	v_writelane_b32 v237, s36, 17
	v_writelane_b32 v237, s37, 18
	v_writelane_b32 v237, s44, 19
	v_writelane_b32 v237, s45, 20
	v_writelane_b32 v237, s82, 21
	v_writelane_b32 v237, s84, 22
	v_writelane_b32 v237, s85, 23
	v_writelane_b32 v237, s90, 24
	v_writelane_b32 v237, s80, 25
	s_add_i32 s80, s95, 0x2c0
	s_movk_i32 s15, 0x60
	s_mov_b32 s94, 1
	v_readlane_b32 s4, v238, 0
	v_readlane_b32 s5, v238, 1
	s_add_u32 s4, s4, 0xfffffee8
	s_addc_u32 s5, s5, -1
	s_load_dwordx2 s[22:23], s[4:5], 0xd8
	s_load_dwordx4 s[24:27], s[4:5], 0xe0
	s_load_dwordx2 s[28:29], s[4:5], 0xf0
	v_readlane_b32 s84, v238, 51
	v_readlane_b32 s85, v238, 52
	v_readlane_b32 s90, v238, 37
	s_waitcnt vmcnt(0) lgkmcnt(0)
	s_branch .Lcvt_entry
.Lp9c_ret:
	v_readlane_b32 s4, v237, 0
	v_readlane_b32 s5, v237, 1
	v_readlane_b32 s6, v237, 2
	v_readlane_b32 s7, v237, 3
	v_readlane_b32 s8, v237, 4
	v_readlane_b32 s9, v237, 5
	v_readlane_b32 s10, v237, 6
	v_readlane_b32 s11, v237, 7
	v_readlane_b32 s12, v237, 8
	v_readlane_b32 s22, v237, 9
	v_readlane_b32 s23, v237, 10
	v_readlane_b32 s24, v237, 11
	v_readlane_b32 s25, v237, 12
	v_readlane_b32 s26, v237, 13
	v_readlane_b32 s27, v237, 14
	v_readlane_b32 s28, v237, 15
	v_readlane_b32 s29, v237, 16
	v_readlane_b32 s36, v237, 17
	v_readlane_b32 s37, v237, 18
	v_readlane_b32 s44, v237, 19
	v_readlane_b32 s45, v237, 20
	v_readlane_b32 s82, v237, 21
	v_readlane_b32 s84, v237, 22
	v_readlane_b32 s85, v237, 23
	v_readlane_b32 s90, v237, 24
	v_readlane_b32 s80, v237, 25
	s_movk_i32 s15, 0x100
	s_nop 4
.Lp9c_skip:
	s_waitcnt vmcnt(0)
	v_lshrrev_b32_e32 v3, 1, v185
	v_lshrrev_b32_e32 v4, 5, v185
	v_and_b32_e32 v3, 24, v3
	v_and_b32_e32 v4, 4, v4
	v_bfe_u32 v5, v185, 2, 2
	v_lshlrev_b32_e32 v1, 4, v185
	v_and_b32_e32 v2, 32, v185
	v_bfe_u32 v152, v185, 2, 4
	v_or3_b32 v3, v4, v5, v3
	v_lshrrev_b32_e32 v4, 3, v185
	s_movk_i32 s0, 0x70
	v_bitop3_b32 v150, v1, v2, 48 bitop3:0x6c
	v_and_b32_e32 v151, 64, v185
	v_and_or_b32 v5, v4, s0, v152
	s_movk_i32 s0, 0x60
	v_add_u32_e32 v153, 0x2000, v1
	v_or_b32_e32 v2, v150, v151
	v_and_or_b32 v4, v4, s0, v3
	v_lshrrev_b32_e32 v1, 7, v153
	s_movk_i32 s0, 0xf0
	v_lshl_or_b32 v130, v4, 12, v2
	v_and_or_b32 v4, v1, s0, v152
	s_movk_i32 s0, 0xe0
	v_bfe_u32 v0, v185, 4, 2
	v_and_or_b32 v1, v1, s0, v3
	v_lshl_or_b32 v134, v1, 12, v2
	v_lshlrev_b32_e32 v154, 3, v0
	v_lshlrev_b32_e32 v156, 4, v0
	v_lshlrev_b32_e32 v0, 6, v185
	v_lshlrev_b32_e32 v1, 2, v185
	v_and_b32_e32 v0, 0x3c0, v0
	v_and_b32_e32 v1, 32, v1
	v_readfirstlane_b32 s3, v185
	v_lshl_or_b32 v128, v5, 12, v2
	v_lshl_or_b32 v132, v4, 12, v2
	v_and_b32_e32 v155, 15, v185
	s_cmpk_gt_i32 s80, 0x7f
	v_bitop3_b32 v157, v156, v1, v0 bitop3:0x36
	s_cbranch_scc1 .LBB0_1307
	s_ashr_i32 s14, s80, 31
	s_lshr_b32 s0, s14, 29
	s_add_i32 s2, s80, s0
	s_and_b32 s0, s2, -8
	s_sub_i32 s13, s80, s0
	s_cmp_gt_i32 s13, -1
	s_cbranch_scc0 .LBB0_1286
	s_lshl_b32 s12, s13, 4
	s_cbranch_execz .LBB0_1287
	s_branch .LBB0_1288
